# baseline (speedup 1.0000x reference)
; #define QK_FENCE() __builtin_amdgcn_sched_barrier(0x406)
; DI void finishSM(f32x16& p0, f32x16& p1, float alpha, float& l_reg, bf16x8& pa0, bf16x8& pa1, bf16x8& pa2, bf16x8& pa3) {
; #pragma unroll
;   for (int r = 0; r < 16; ++r) p1[r] = __builtin_amdgcn_exp2f(p1[r]);
;   float ps = 0;
; #pragma unroll
;   for (int r = 0; r < 16; ++r) ps += p0[r];
; #pragma unroll
;   for (int r = 0; r < 16; ++r) ps += p1[r];
;   { auto rr = __builtin_amdgcn_permlane32_swap(__float_as_uint(ps), __float_as_uint(ps), false, false);
;     ps = __uint_as_float(rr[0]) + __uint_as_float(rr[1]); }
;   l_reg = l_reg * alpha + ps;
;     ...
;   PK4(p0, 0, pa0); PK4(p0, 8, pa1); PK4(p1, 0, pa2); PK4(p1, 8, pa3);
; DI void qkt12(f32x16& p0, f32x16& p1, const char* Kt, const char* Rt, const int* ko, const int* ro, const bf16x8* qr) {
;   { const f32x16 z = {0.f, 0.f, 0.f, 0.f, 0.f, 0.f, 0.f, 0.f, 0.f, 0.f, 0.f, 0.f, 0.f, 0.f, 0.f, 0.f}; p0 = z; p1 = z; }
;   const char* kp[4] = {Kt + ko[0], Kt + ko[1], Kt + ko[2], Kt + ko[3]};
;   const char* rp[4] = {Rt + ro[0], Rt + ro[1], Rt + ro[2], Rt + ro[3]};
;   bf16x8 ka[2], kb[2];
;   ka[0] = *reinterpret_cast<const bf16x8*>(kp[0]); kb[0] = *reinterpret_cast<const bf16x8*>(kp[0] + 8192);
; #pragma unroll
;   for (int d0 = 0; d0 < 12; ++d0) {
;     if (d0 + 1 < 12) { const int d1 = d0 + 1;
;       if (d1 < 8) { ka[d1 & 1] = *reinterpret_cast<const bf16x8*>(kp[d1 & 3] + (d1 >> 2) * 128); kb[d1 & 1] = *reinterpret_cast<const bf16x8*>(kp[d1 & 3] + (d1 >> 2) * 128 + 8192); }
;       else { ka[d1 & 1] = *reinterpret_cast<const bf16x8*>(rp[d1 - 8]); kb[d1 & 1] = *reinterpret_cast<const bf16x8*>(rp[d1 - 8] + 4096); } }
;     QK_FENCE();
;     p0 = __builtin_amdgcn_mfma_f32_32x32x16_bf16(ka[d0 & 1], qr[d0], p0, 0, 0, 0);
;     p1 = __builtin_amdgcn_mfma_f32_32x32x16_bf16(kb[d0 & 1], qr[d0], p1, 0, 0, 0);
;     QK_FENCE();
;   }
.LBB0_122:
	v_sub_co_u32_e64 v64, s[6:7], s61, 1
	s_and_b64 s[6:7], s[6:7], exec
	v_readfirstlane_b32 s2, v64
	s_cselect_b32 s13, 2, s2
	s_mul_i32 s42, s61, 0xa000
	s_add_i32 s45, s42, 16
	v_add_u32_e32 v177, s45, v176
	ds_read_b128 v[64:67], v177 offset:16384
	v_add_u32_e32 v220, s45, v179
	ds_read_b128 v[68:71], v177 offset:24576
	ds_read_b128 v[188:191], v220 offset:16384
	ds_read_b128 v[208:211], v220 offset:24576
	v_add_u32_e32 v221, s45, v180
	v_add_u32_e32 v222, s45, v181
	v_exp_f32_e32 v200, v200
	v_exp_f32_e32 v202, v202
	v_exp_f32_e32 v201, v201
	v_exp_f32_e32 v204, v204
	v_exp_f32_e32 v203, v203
	v_exp_f32_e32 v206, v206
	v_exp_f32_e32 v205, v205
	v_exp_f32_e32 v207, v207
	v_exp_f32_e32 v192, v192
	v_exp_f32_e32 v194, v194
	v_exp_f32_e32 v193, v193
	v_exp_f32_e32 v196, v196
	v_exp_f32_e32 v195, v195
	v_exp_f32_e32 v198, v198
	v_exp_f32_e32 v197, v197
	v_exp_f32_e32 v199, v199
	v_exp_f32_e32 v166, v166
	s_waitcnt lgkmcnt(3)
	v_mfma_f32_32x32x16_bf16 v[80:95], v[64:67], v[134:137], 0
	v_exp_f32_e32 v167, v167
	v_exp_f32_e32 v163, v163
	v_exp_f32_e32 v168, v168
	v_mfma_f32_32x32x16_bf16 v[64:79], v[68:71], v[134:137], 0
	ds_read_b128 v[212:215], v221 offset:16384
	ds_read_b128 v[216:219], v221 offset:24576
	v_exp_f32_e32 v169, v169
	v_exp_f32_e32 v235, v162
	v_exp_f32_e32 v237, v164
	s_waitcnt lgkmcnt(2)
	v_mfma_f32_32x32x16_bf16 v[64:79], v[208:211], v[130:133], v[64:79]
	v_exp_f32_e32 v241, v165
	v_exp_f32_e32 v243, v158
	v_exp_f32_e32 v244, v159
	v_mfma_f32_32x32x16_bf16 v[80:95], v[188:191], v[130:133], v[80:95]
	ds_read_b128 v[188:191], v222 offset:16384
	ds_read_b128 v[208:211], v222 offset:24576
	v_exp_f32_e32 v245, v154
	v_add_f32_e32 v154, 0, v200
	v_add_f32_e32 v154, v202, v154
	v_add_f32_e32 v154, v201, v154
	v_add_f32_e32 v154, v204, v154
	s_waitcnt lgkmcnt(2)
	v_mfma_f32_32x32x16_bf16 v[64:79], v[216:219], v[126:129], v[64:79]
	s_add_i32 s2, s42, 0xa000
	s_cmp_lg_u32 s61, 2
	s_cselect_b32 s2, s2, 0
	v_add_u32_e32 v240, s2, v178
	s_add_u32 s0, s82, 0x1bbc0100
	s_addc_u32 s1, s83, 0
	v_lshl_add_u64 v[238:239], v[150:151], 0, s[0:1]
	v_readfirstlane_b32 s2, v240
	s_mov_b32 m0, s2
	v_add_f32_e32 v154, v203, v154
	global_load_lds_dwordx4 v[238:239], off
	v_add_f32_e32 v154, v206, v154
	v_add_f32_e32 v154, v205, v154
	v_mfma_f32_32x32x16_bf16 v[80:95], v[212:215], v[126:129], v[80:95]
	ds_read_b128 v[212:215], v177 offset:16512
	ds_read_b128 v[216:219], v177 offset:24704
	v_add_u32_e32 v177, s45, v182
	v_add_f32_e32 v154, v207, v154
	v_add_f32_e32 v154, v192, v154
	v_add_f32_e32 v154, v194, v154
	v_add_f32_e32 v154, v193, v154
	v_add_f32_e32 v154, v196, v154
	s_waitcnt lgkmcnt(2)
	v_mfma_f32_32x32x16_bf16 v[64:79], v[208:211], v[114:117], v[64:79]
	v_add_f32_e32 v154, v195, v154
	v_add_f32_e32 v154, v198, v154
	v_add_f32_e32 v154, v197, v154
	v_add_f32_e32 v154, v199, v154
	v_exp_f32_e32 v246, v160
	v_mfma_f32_32x32x16_bf16 v[80:95], v[188:191], v[114:117], v[80:95]
	ds_read_b128 v[188:191], v220 offset:16512
	ds_read_b128 v[208:211], v220 offset:24704
	v_add_f32_e32 v154, v166, v154
	v_exp_f32_e32 v248, v161
	v_add_f32_e32 v154, v167, v154
	v_exp_f32_e32 v249, v156
	s_waitcnt lgkmcnt(2)
	v_mfma_f32_32x32x16_bf16 v[64:79], v[216:219], v[110:113], v[64:79]
	v_add_u32_e32 v242, 0x2000, v240
	s_add_u32 s0, s82, 0x1bbe0100
	s_addc_u32 s1, s83, 0
	v_lshl_add_u64 v[238:239], v[150:151], 0, s[0:1]
	v_readfirstlane_b32 s2, v242
	s_mov_b32 m0, s2
	v_add_f32_e32 v154, v235, v154
	global_load_lds_dwordx4 v[238:239], off
	v_exp_f32_e32 v250, v157
	v_mfma_f32_32x32x16_bf16 v[80:95], v[212:215], v[110:113], v[80:95]
	ds_read_b128 v[212:215], v221 offset:16512
	ds_read_b128 v[216:219], v221 offset:24704
	v_add_f32_e32 v154, v163, v154
	v_add_f32_e32 v154, v246, v154
	v_exp_f32_e32 v251, v155
	v_add_f32_e32 v154, v248, v154
	v_add_f32_e32 v154, v249, v154
	s_waitcnt lgkmcnt(2)
	v_mfma_f32_32x32x16_bf16 v[64:79], v[208:211], v[106:109], v[64:79]
	v_add_f32_e32 v154, v250, v154
	v_add_f32_e32 v154, v245, v154
	v_add_f32_e32 v154, v251, v154
	v_add_f32_e32 v154, v168, v154
	v_add_f32_e32 v154, v169, v154
	v_add_f32_e32 v154, v237, v154
	v_mfma_f32_32x32x16_bf16 v[80:95], v[188:191], v[106:109], v[80:95]
	ds_read_b128 v[188:191], v222 offset:16512
	ds_read_b128 v[208:211], v222 offset:24704
	v_add_f32_e32 v154, v241, v154
	v_add_f32_e32 v154, v243, v154
	v_cvt_pk_bf16_f32 v155, v201, v204
	v_cvt_pk_bf16_f32 v156, v203, v206
	v_cvt_pk_bf16_f32 v157, v205, v207
	v_cvt_pk_bf16_f32 v158, v192, v194
	s_waitcnt lgkmcnt(2)
	v_mfma_f32_32x32x16_bf16 v[64:79], v[216:219], v[102:105], v[64:79]
	v_add_u32_e32 v242, 0x4000, v240
	s_add_u32 s0, s82, 0x1bbc0000
	s_addc_u32 s1, s83, 0
	v_lshl_add_u64 v[238:239], v[152:153], 0, s[0:1]
	v_readfirstlane_b32 s2, v242
	s_mov_b32 m0, s2
	v_cvt_pk_bf16_f32 v159, v193, v196
	global_load_lds_dwordx4 v[238:239], off
	v_cvt_pk_bf16_f32 v160, v195, v198
	v_cvt_pk_bf16_f32 v161, v197, v199
	v_mfma_f32_32x32x16_bf16 v[80:95], v[212:215], v[102:105], v[80:95]
	ds_read_b128 v[212:215], v177 offset:32768
	ds_read_b128 v[216:219], v177 offset:36864
	v_add_u32_e32 v177, s45, v183
	v_permlane32_swap_b32_e32 v155, v157
	v_permlane32_swap_b32_e32 v158, v160
	v_permlane32_swap_b32_e32 v159, v161
	v_cvt_pk_bf16_f32 v162, v166, v167
	v_cvt_pk_bf16_f32 v163, v235, v163
	s_waitcnt lgkmcnt(2)
	v_mfma_f32_32x32x16_bf16 v[64:79], v[208:211], v[98:101], v[64:79]
	v_cvt_pk_bf16_f32 v164, v246, v248
	v_cvt_pk_bf16_f32 v165, v249, v250
	v_cvt_pk_bf16_f32 v166, v245, v251
	v_cvt_pk_bf16_f32 v167, v168, v169
	v_cvt_pk_bf16_f32 v168, v237, v241
	v_cvt_pk_bf16_f32 v169, v243, v244
	v_mfma_f32_32x32x16_bf16 v[80:95], v[188:191], v[98:101], v[80:95]
	ds_read_b128 v[188:191], v177 offset:32768
	ds_read_b128 v[208:211], v177 offset:36864
	v_add_u32_e32 v177, s45, v184
	v_permlane32_swap_b32_e32 v162, v164
	v_permlane32_swap_b32_e32 v163, v165
	v_permlane32_swap_b32_e32 v166, v168
	v_permlane32_swap_b32_e32 v167, v169
	s_waitcnt lgkmcnt(2)
; #define SBAR() __builtin_amdgcn_sched_barrier(0)
; #define QK_FENCE() __builtin_amdgcn_sched_barrier(0x406)
; template <int D0> DI void pv_one(f32x16& od, int vb, bf16x8 pa0, bf16x8 pa1, bf16x8 pa2, bf16x8 pa3) {
;   const s16x4 l0 = tr_read<v_rd_off(D0, 0, 0)>(vb), h0 = tr_read<v_rd_off(D0, 0, 1)>(vb), l1 = tr_read<v_rd_off(D0, 1, 0)>(vb), h1 = tr_read<v_rd_off(D0, 1, 1)>(vb);
;   const s16x4 l2 = tr_read<v_rd_off(D0, 2, 0)>(vb), h2 = tr_read<v_rd_off(D0, 2, 1)>(vb), l3 = tr_read<v_rd_off(D0, 3, 0)>(vb), h3 = tr_read<v_rd_off(D0, 3, 1)>(vb);
;   asm volatile("s_waitcnt lgkmcnt(0)" ::: "memory"); SBAR();
;     ...
;   od = __builtin_amdgcn_mfma_f32_32x32x16_bf16(pa0, PK(l0, h0), od, 0, 0, 0);
;   od = __builtin_amdgcn_mfma_f32_32x32x16_bf16(pa1, PK(l1, h1), od, 0, 0, 0);
;   od = __builtin_amdgcn_mfma_f32_32x32x16_bf16(pa2, PK(l2, h2), od, 0, 0, 0);
;   od = __builtin_amdgcn_mfma_f32_32x32x16_bf16(pa3, PK(l3, h3), od, 0, 0, 0);
;     ...
; }
; DI void pv_d0(f32x16* o, int vb, bf16x8 pa0, bf16x8 pa1, bf16x8 pa2, bf16x8 pa3) {
;   pv_one<0>(o[0], vb, pa0, pa1, pa2, pa3); pv_one<1>(o[1], vb, pa0, pa1, pa2, pa3); pv_one<2>(o[2], vb, pa0, pa1, pa2, pa3); pv_one<3>(o[3], vb, pa0, pa1, pa2, pa3);
; DI void qkt12(f32x16& p0, f32x16& p1, const char* Kt, const char* Rt, const int* ko, const int* ro, const bf16x8* qr) {
;   { const f32x16 z = {0.f, 0.f, 0.f, 0.f, 0.f, 0.f, 0.f, 0.f, 0.f, 0.f, 0.f, 0.f, 0.f, 0.f, 0.f, 0.f}; p0 = z; p1 = z; }
;   const char* kp[4] = {Kt + ko[0], Kt + ko[1], Kt + ko[2], Kt + ko[3]};
;   const char* rp[4] = {Rt + ro[0], Rt + ro[1], Rt + ro[2], Rt + ro[3]};
;   bf16x8 ka[2], kb[2];
;   ka[0] = *reinterpret_cast<const bf16x8*>(kp[0]); kb[0] = *reinterpret_cast<const bf16x8*>(kp[0] + 8192);
; #pragma unroll
;   for (int d0 = 0; d0 < 12; ++d0) {
;     if (d0 + 1 < 12) { const int d1 = d0 + 1;
;       if (d1 < 8) { ka[d1 & 1] = *reinterpret_cast<const bf16x8*>(kp[d1 & 3] + (d1 >> 2) * 128); kb[d1 & 1] = *reinterpret_cast<const bf16x8*>(kp[d1 & 3] + (d1 >> 2) * 128 + 8192); }
;       else { ka[d1 & 1] = *reinterpret_cast<const bf16x8*>(rp[d1 - 8]); kb[d1 & 1] = *reinterpret_cast<const bf16x8*>(rp[d1 - 8] + 4096); } }
;     QK_FENCE();
;     p0 = __builtin_amdgcn_mfma_f32_32x32x16_bf16(ka[d0 & 1], qr[d0], p0, 0, 0, 0);
;     p1 = __builtin_amdgcn_mfma_f32_32x32x16_bf16(kb[d0 & 1], qr[d0], p1, 0, 0, 0);
;     QK_FENCE();
;   }
	v_mfma_f32_32x32x16_bf16 v[64:79], v[216:219], v[122:125], v[64:79]
	v_add_u32_e32 v242, 0x6000, v240
	s_add_u32 s0, s82, 0x1bbe0000
	s_addc_u32 s1, s83, 0
	v_lshl_add_u64 v[238:239], v[152:153], 0, s[0:1]
	v_readfirstlane_b32 s2, v242
	s_mov_b32 m0, s2
	s_nop 0
	global_load_lds_dwordx4 v[238:239], off
	v_mfma_f32_32x32x16_bf16 v[80:95], v[212:215], v[122:125], v[80:95]
	ds_read_b128 v[212:215], v177 offset:32768
	ds_read_b128 v[216:219], v177 offset:36864
	v_add_u32_e32 v177, s45, v185
	s_waitcnt lgkmcnt(2)
	v_mfma_f32_32x32x16_bf16 v[64:79], v[208:211], v[142:145], v[64:79]
	v_mfma_f32_32x32x16_bf16 v[80:95], v[188:191], v[142:145], v[80:95]
	ds_read_b128 v[188:191], v177 offset:32768
	ds_read_b128 v[208:211], v177 offset:36864
	s_waitcnt lgkmcnt(2)
	v_mfma_f32_32x32x16_bf16 v[64:79], v[216:219], v[118:121], v[64:79]
	v_add_u32_e32 v242, 0x8000, v240
	s_add_u32 s0, s82, 0x1fb44000
	s_addc_u32 s1, s83, 0
	v_lshl_add_u64 v[238:239], v[148:149], 0, s[0:1]
	v_readfirstlane_b32 s2, v242
	s_mov_b32 m0, s2
	s_nop 0
	global_load_lds_dwordx4 v[238:239], off
	s_movk_i32 s0, 0x410
	s_movk_i32 s1, 0x1800
	v_mfma_f32_32x32x16_bf16 v[80:95], v[212:215], v[118:121], v[80:95]
	s_waitcnt lgkmcnt(0)
	v_mfma_f32_32x32x16_bf16 v[64:79], v[208:211], v[138:141], v[64:79]
	v_mfma_f32_32x32x16_bf16 v[80:95], v[188:191], v[138:141], v[80:95]
	s_mul_i32 s44, s13, 0xa000
	v_add_u32_e32 v177, s44, v174
	ds_read_b64_tr_b16 v[190:191], v177 offset:0
	ds_read_b64_tr_b16 v[192:193], v177 offset:0x800
	ds_read_b64_tr_b16 v[194:195], v177 offset:0x1000
	ds_read_b64_tr_b16 v[196:197], v177 offset:0x1800
	ds_read_b64_tr_b16 v[198:199], v177 offset:0x2000
	v_add_f32_e32 v188, v244, v154
	v_mov_b32_e32 v189, v188
	v_cvt_pk_bf16_f32 v154, v200, v202
	ds_read_b64_tr_b16 v[200:201], v177 offset:0x2800
	ds_read_b64_tr_b16 v[202:203], v177 offset:0x3000
	ds_read_b64_tr_b16 v[204:205], v177 offset:0x3800
	v_permlane32_swap_b32_e32 v188, v189
	v_permlane32_swap_b32_e32 v154, v156
	s_waitcnt lgkmcnt(6)
	v_max_f32_e32 v235, v81, v81
	v_mfma_f32_32x32x16_bf16 v[0:15], v[154:157], v[190:193], v[0:15]
	ds_read_b64_tr_b16 v[190:191], v177 offset:0x200
	ds_read_b64_tr_b16 v[192:193], v177 offset:0xa00
	v_max_f32_e32 v237, v80, v80
	v_max_f32_e32 v235, v237, v235
	v_max3_f32 v235, v235, v82, v83
	v_max3_f32 v235, v235, v84, v85
	v_max3_f32 v235, v235, v86, v87
	v_max3_f32 v235, v235, v88, v89
	s_waitcnt lgkmcnt(6)
	v_mfma_f32_32x32x16_bf16 v[0:15], v[158:161], v[194:197], v[0:15]
	ds_read_b64_tr_b16 v[194:195], v177 offset:0x1200
	ds_read_b64_tr_b16 v[196:197], v177 offset:0x1a00
	v_max3_f32 v235, v235, v90, v91
	v_max3_f32 v235, v235, v92, v93
	v_max3_f32 v235, v235, v94, v95
	v_max3_f32 v235, v235, v64, v65
	v_max3_f32 v235, v235, v66, v67
	v_max3_f32 v235, v235, v68, v69
	s_waitcnt lgkmcnt(6)
	v_mfma_f32_32x32x16_bf16 v[0:15], v[162:165], v[198:201], v[0:15]
	ds_read_b64_tr_b16 v[198:199], v177 offset:0x2200
	ds_read_b64_tr_b16 v[200:201], v177 offset:0x2a00
	v_max3_f32 v235, v235, v70, v71
	v_max3_f32 v235, v235, v72, v73
	v_max3_f32 v235, v235, v74, v75
	v_max3_f32 v235, v235, v76, v77
	v_max3_f32 v235, v235, v78, v79
	v_mov_b32_e32 v237, v235
	s_waitcnt lgkmcnt(6)
	v_mfma_f32_32x32x16_bf16 v[0:15], v[166:169], v[202:205], v[0:15]
	ds_read_b64_tr_b16 v[202:203], v177 offset:0x3200
	ds_read_b64_tr_b16 v[204:205], v177 offset:0x3a00
	v_permlane32_swap_b32_e32 v235, v237
	v_max_f32_e32 v237, v237, v237
	v_max_f32_e32 v235, v235, v235
	s_waitcnt lgkmcnt(6)
	v_mfma_f32_32x32x16_bf16 v[48:63], v[154:157], v[190:193], v[48:63]
	ds_read_b64_tr_b16 v[190:191], v177 offset:0x400
	ds_read_b64_tr_b16 v[192:193], v177 offset:0xc00
	s_waitcnt lgkmcnt(6)
	v_mfma_f32_32x32x16_bf16 v[48:63], v[158:161], v[194:197], v[48:63]
	ds_read_b64_tr_b16 v[194:195], v177 offset:0x1400
	ds_read_b64_tr_b16 v[196:197], v177 offset:0x1c00
	s_waitcnt lgkmcnt(6)
	v_mfma_f32_32x32x16_bf16 v[48:63], v[162:165], v[198:201], v[48:63]
	ds_read_b64_tr_b16 v[198:199], v177 offset:0x2400
	ds_read_b64_tr_b16 v[200:201], v177 offset:0x2c00
	s_waitcnt lgkmcnt(6)
	v_mfma_f32_32x32x16_bf16 v[48:63], v[166:169], v[202:205], v[48:63]
	ds_read_b64_tr_b16 v[202:203], v177 offset:0x3400
	ds_read_b64_tr_b16 v[204:205], v177 offset:0x3c00
	s_waitcnt lgkmcnt(6)
	v_mfma_f32_32x32x16_bf16 v[32:47], v[154:157], v[190:193], v[32:47]
	ds_read_b64_tr_b16 v[190:191], v177 offset:0x600
	ds_read_b64_tr_b16 v[192:193], v177 offset:0xe00
	s_waitcnt lgkmcnt(6)
	v_mfma_f32_32x32x16_bf16 v[32:47], v[158:161], v[194:197], v[32:47]
	ds_read_b64_tr_b16 v[194:195], v177 offset:0x1600
	ds_read_b64_tr_b16 v[196:197], v177 offset:0x1e00
	s_waitcnt lgkmcnt(6)
	v_mfma_f32_32x32x16_bf16 v[32:47], v[162:165], v[198:201], v[32:47]
	ds_read_b64_tr_b16 v[198:199], v177 offset:0x2600
	ds_read_b64_tr_b16 v[200:201], v177 offset:0x2e00
	s_waitcnt lgkmcnt(6)
	v_mfma_f32_32x32x16_bf16 v[32:47], v[166:169], v[202:205], v[32:47]
	ds_read_b64_tr_b16 v[202:203], v177 offset:0x3600
	ds_read_b64_tr_b16 v[204:205], v177 offset:0x3e00
	s_waitcnt vmcnt(0)
	s_waitcnt lgkmcnt(0)
	s_barrier
	v_mfma_f32_32x32x16_bf16 v[16:31], v[154:157], v[190:193], v[16:31]
	v_mfma_f32_32x32x16_bf16 v[16:31], v[158:161], v[194:197], v[16:31]
	v_max_f32_e32 v160, v235, v237
	v_sub_f32_e32 v235, v160, v187
	v_mfma_f32_32x32x16_bf16 v[16:31], v[162:165], v[198:201], v[16:31]
	v_mfma_f32_32x32x16_bf16 v[16:31], v[166:169], v[202:205], v[16:31]
	v_cmp_ge_f32_e32 vcc, s65, v235
	s_cmp_eq_u64 vcc, exec
	s_waitcnt vmcnt(0)
	s_cselect_b64 s[38:39], -1, 0
	s_add_i32 s2, s12, -1
	s_cmp_ge_u32 s2, s52
	v_lshl_add_u64 v[158:159], v[150:151], 0, s[82:83]
	v_lshl_add_u64 v[156:157], v[152:153], 0, s[82:83]
	v_lshl_add_u64 v[154:155], v[148:149], 0, s[82:83]

; #define QK_FENCE() __builtin_amdgcn_sched_barrier(0x406)
; DI void partialSM(f32x16& p0, f32x16& p1, float& m_reg, float& mn, float& alpha) {
;     ...
;   const float mnC = -mn * C;
; #pragma unroll
;   for (int r = 0; r < 16; ++r) p0[r] = fmaf(p0[r], C, mnC);
; #pragma unroll
;   for (int r = 0; r < 16; ++r) p1[r] = fmaf(p1[r], C, mnC);
; #pragma unroll
;   for (int r = 0; r < 16; ++r) p0[r] = __builtin_amdgcn_exp2f(p0[r]);
; }
; DI void finishSM(f32x16& p0, f32x16& p1, float alpha, float& l_reg, bf16x8& pa0, bf16x8& pa1, bf16x8& pa2, bf16x8& pa3) {
; #pragma unroll
;   for (int r = 0; r < 16; ++r) p1[r] = __builtin_amdgcn_exp2f(p1[r]);
;   float ps = 0;
; #pragma unroll
;   for (int r = 0; r < 16; ++r) ps += p0[r];
; #pragma unroll
;   for (int r = 0; r < 16; ++r) ps += p1[r];
;   { auto rr = __builtin_amdgcn_permlane32_swap(__float_as_uint(ps), __float_as_uint(ps), false, false);
;     ps = __uint_as_float(rr[0]) + __uint_as_float(rr[1]); }
;   l_reg = l_reg * alpha + ps;
; DI void qkt12(f32x16& p0, f32x16& p1, const char* Kt, const char* Rt, const int* ko, const int* ro, const bf16x8* qr) {
;   { const f32x16 z = {0.f, 0.f, 0.f, 0.f, 0.f, 0.f, 0.f, 0.f, 0.f, 0.f, 0.f, 0.f, 0.f, 0.f, 0.f, 0.f}; p0 = z; p1 = z; }
;   const char* kp[4] = {Kt + ko[0], Kt + ko[1], Kt + ko[2], Kt + ko[3]};
;   const char* rp[4] = {Rt + ro[0], Rt + ro[1], Rt + ro[2], Rt + ro[3]};
;   bf16x8 ka[2], kb[2];
;   ka[0] = *reinterpret_cast<const bf16x8*>(kp[0]); kb[0] = *reinterpret_cast<const bf16x8*>(kp[0] + 8192);
; #pragma unroll
;   for (int d0 = 0; d0 < 12; ++d0) {
;     if (d0 + 1 < 12) { const int d1 = d0 + 1;
;       if (d1 < 8) { ka[d1 & 1] = *reinterpret_cast<const bf16x8*>(kp[d1 & 3] + (d1 >> 2) * 128); kb[d1 & 1] = *reinterpret_cast<const bf16x8*>(kp[d1 & 3] + (d1 >> 2) * 128 + 8192); }
;       else { ka[d1 & 1] = *reinterpret_cast<const bf16x8*>(rp[d1 - 8]); kb[d1 & 1] = *reinterpret_cast<const bf16x8*>(rp[d1 - 8] + 4096); } }
;     QK_FENCE();
;     p0 = __builtin_amdgcn_mfma_f32_32x32x16_bf16(ka[d0 & 1], qr[d0], p0, 0, 0, 0);
;     p1 = __builtin_amdgcn_mfma_f32_32x32x16_bf16(kb[d0 & 1], qr[d0], p1, 0, 0, 0);
;     QK_FENCE();
;   }
.LBB0_128:
	s_add_i32 s2, s12, -1
	s_cmp_ge_u32 s2, s52
	s_cbranch_scc1 .Lattn_bb2_nodma
	v_cndmask_b32_e64 v160, v160, v187, s[38:39]
	s_add_i32 s2, s42, 0xa000
	s_cmp_lg_u32 s61, 2
	s_cselect_b32 s2, s2, 0
	s_add_i32 s6, s2, 16
	v_add_u32_e32 v213, s6, v176
	ds_read_b128 v[222:225], v213 offset:16384
	v_add_u32_e32 v230, s6, v179
	ds_read_b128 v[226:229], v213 offset:24576
	ds_read_b128 v[214:217], v230 offset:16384
	ds_read_b128 v[218:221], v230 offset:24576
	v_add_u32_e32 v231, s6, v180
	v_add_u32_e32 v234, s6, v181
	v_mul_f32_e32 v197, 0xbdd53b94, v160
	v_fmamk_f32 v161, v94, 0x3dd53b94, v197
	v_fmamk_f32 v194, v80, 0x3dd53b94, v197
	v_fmamk_f32 v196, v81, 0x3dd53b94, v197
	v_fmamk_f32 v192, v82, 0x3dd53b94, v197
	v_fmamk_f32 v195, v83, 0x3dd53b94, v197
	v_fmamk_f32 v187, v84, 0x3dd53b94, v197
	v_fmamk_f32 v193, v85, 0x3dd53b94, v197
	v_fmamk_f32 v169, v86, 0x3dd53b94, v197
	v_fmamk_f32 v190, v87, 0x3dd53b94, v197
	v_fmamk_f32 v166, v88, 0x3dd53b94, v197
	v_fmamk_f32 v168, v89, 0x3dd53b94, v197
	v_fmamk_f32 v164, v90, 0x3dd53b94, v197
	v_fmamk_f32 v167, v91, 0x3dd53b94, v197
	v_fmamk_f32 v162, v92, 0x3dd53b94, v197
	v_fmamk_f32 v165, v93, 0x3dd53b94, v197
	v_fmamk_f32 v163, v95, 0x3dd53b94, v197
	v_fmamk_f32 v208, v74, 0x3dd53b94, v197
	v_fmamk_f32 v209, v75, 0x3dd53b94, v197
	v_fmamk_f32 v198, v64, 0x3dd53b94, v197
	v_fmamk_f32 v199, v65, 0x3dd53b94, v197
	v_fmamk_f32 v200, v66, 0x3dd53b94, v197
	v_fmamk_f32 v201, v67, 0x3dd53b94, v197
	v_fmamk_f32 v202, v68, 0x3dd53b94, v197
	v_fmamk_f32 v203, v69, 0x3dd53b94, v197
	v_fmamk_f32 v204, v70, 0x3dd53b94, v197
	v_fmamk_f32 v205, v71, 0x3dd53b94, v197
	v_fmamk_f32 v206, v72, 0x3dd53b94, v197
	v_fmamk_f32 v207, v73, 0x3dd53b94, v197
	v_fmamk_f32 v210, v76, 0x3dd53b94, v197
	v_fmamk_f32 v211, v77, 0x3dd53b94, v197
	v_fmamk_f32 v212, v78, 0x3dd53b94, v197
	v_fmac_f32_e32 v197, 0x3dd53b94, v79
	v_exp_f32_e32 v161, v161
	s_waitcnt lgkmcnt(3)
	v_mfma_f32_32x32x16_bf16 v[80:95], v[222:225], v[134:137], 0
	v_exp_f32_e32 v194, v194
	v_exp_f32_e32 v196, v196
	v_exp_f32_e32 v192, v192
	s_waitcnt lgkmcnt(2)
	v_mfma_f32_32x32x16_bf16 v[64:79], v[226:229], v[134:137], 0
	ds_read_b128 v[222:225], v231 offset:16384
	ds_read_b128 v[226:229], v231 offset:24576
	v_exp_f32_e32 v195, v195
	v_exp_f32_e32 v187, v187
	v_exp_f32_e32 v193, v193
	s_waitcnt lgkmcnt(3)
	v_mfma_f32_32x32x16_bf16 v[80:95], v[214:217], v[130:133], v[80:95]
	v_exp_f32_e32 v169, v169
	v_exp_f32_e32 v190, v190
	v_exp_f32_e32 v166, v166
	s_waitcnt lgkmcnt(2)
	v_mfma_f32_32x32x16_bf16 v[64:79], v[218:221], v[130:133], v[64:79]
	ds_read_b128 v[214:217], v234 offset:16384
	ds_read_b128 v[218:221], v234 offset:24576
	v_exp_f32_e32 v168, v168
	v_exp_f32_e32 v164, v164
	v_exp_f32_e32 v167, v167
	s_waitcnt lgkmcnt(3)
	v_mfma_f32_32x32x16_bf16 v[80:95], v[222:225], v[126:129], v[80:95]
	v_add_u32_e32 v240, s44, v178
	v_exp_f32_e32 v162, v162
	v_readfirstlane_b32 s2, v240
	s_mov_b64 s[0:1], 0x1bc00100
	v_lshl_add_u64 v[238:239], v[158:159], 0, s[0:1]
	s_mov_b32 m0, s2
	v_exp_f32_e32 v165, v165
	global_load_lds_dwordx4 v[238:239], off
	s_waitcnt lgkmcnt(2)
	v_mfma_f32_32x32x16_bf16 v[64:79], v[226:229], v[126:129], v[64:79]
	ds_read_b128 v[222:225], v213 offset:16512
	ds_read_b128 v[226:229], v213 offset:24704
	v_add_u32_e32 v213, s6, v182
	v_exp_f32_e32 v163, v163
	v_exp_f32_e32 v198, v198
	s_waitcnt lgkmcnt(3)
	v_mfma_f32_32x32x16_bf16 v[80:95], v[214:217], v[114:117], v[80:95]
	v_exp_f32_e32 v199, v199
	v_exp_f32_e32 v200, v200
	v_exp_f32_e32 v201, v201
	s_waitcnt lgkmcnt(2)
	v_mfma_f32_32x32x16_bf16 v[64:79], v[218:221], v[114:117], v[64:79]
	ds_read_b128 v[214:217], v230 offset:16512
	ds_read_b128 v[218:221], v230 offset:24704
	v_exp_f32_e32 v202, v202
	v_exp_f32_e32 v203, v203
	v_exp_f32_e32 v204, v204
	s_waitcnt lgkmcnt(3)
	v_mfma_f32_32x32x16_bf16 v[80:95], v[222:225], v[110:113], v[80:95]
	v_add_u32_e32 v242, 0x2000, v240
	s_mov_b64 s[0:1], 0x1bc20100
	v_lshl_add_u64 v[238:239], v[158:159], 0, s[0:1]
	v_readfirstlane_b32 s2, v242
	s_mov_b32 m0, s2
	v_exp_f32_e32 v205, v205
	global_load_lds_dwordx4 v[238:239], off
	s_waitcnt lgkmcnt(2)
	v_mfma_f32_32x32x16_bf16 v[64:79], v[226:229], v[110:113], v[64:79]
	ds_read_b128 v[222:225], v231 offset:16512
	ds_read_b128 v[226:229], v231 offset:24704
	v_exp_f32_e32 v206, v206
	v_exp_f32_e32 v207, v207
	v_exp_f32_e32 v210, v210
	s_waitcnt lgkmcnt(3)
	v_mfma_f32_32x32x16_bf16 v[80:95], v[214:217], v[106:109], v[80:95]
	v_exp_f32_e32 v211, v211
	v_exp_f32_e32 v212, v212
	v_exp_f32_e32 v235, v208
	s_waitcnt lgkmcnt(2)
	v_mfma_f32_32x32x16_bf16 v[64:79], v[218:221], v[106:109], v[64:79]
	ds_read_b128 v[214:217], v234 offset:16512
	ds_read_b128 v[218:221], v234 offset:24704
	v_exp_f32_e32 v237, v197
	v_add_f32_e32 v197, 0, v194
	v_add_f32_e32 v197, v196, v197
	v_add_f32_e32 v197, v192, v197
	v_add_f32_e32 v197, v195, v197
	s_waitcnt lgkmcnt(3)
	v_mfma_f32_32x32x16_bf16 v[80:95], v[222:225], v[102:105], v[80:95]
	v_add_u32_e32 v242, 0x4000, v240
	s_mov_b64 s[0:1], 0x1bc00000
	v_lshl_add_u64 v[238:239], v[156:157], 0, s[0:1]
	v_readfirstlane_b32 s2, v242
	s_mov_b32 m0, s2
	v_add_f32_e32 v197, v187, v197
	global_load_lds_dwordx4 v[238:239], off
	v_add_f32_e32 v197, v193, v197
	v_add_f32_e32 v197, v169, v197
	s_waitcnt lgkmcnt(2)
	v_mfma_f32_32x32x16_bf16 v[64:79], v[226:229], v[102:105], v[64:79]
	ds_read_b128 v[222:225], v213 offset:32768
	ds_read_b128 v[226:229], v213 offset:36864
	v_add_u32_e32 v213, s6, v183
	v_add_f32_e32 v197, v190, v197
	v_add_f32_e32 v197, v166, v197
	v_add_f32_e32 v197, v168, v197
	v_add_f32_e32 v197, v164, v197
	v_add_f32_e32 v197, v167, v197
	s_waitcnt lgkmcnt(3)
; #define SBAR() __builtin_amdgcn_sched_barrier(0)
; template <int OFF> DI s16x4 tr_read(int vb) { s16x4 r; asm volatile("ds_read_b64_tr_b16 %0, %1 offset:%2" : "=&v"(r) : "v"(vb), "i"(OFF) : "memory"); return r; }
; DI void finishSM(f32x16& p0, f32x16& p1, float alpha, float& l_reg, bf16x8& pa0, bf16x8& pa1, bf16x8& pa2, bf16x8& pa3) {
;     ...
;   float ps = 0;
; #pragma unroll
;   for (int r = 0; r < 16; ++r) ps += p0[r];
; #pragma unroll
;   for (int r = 0; r < 16; ++r) ps += p1[r];
;   { auto rr = __builtin_amdgcn_permlane32_swap(__float_as_uint(ps), __float_as_uint(ps), false, false);
;     ps = __uint_as_float(rr[0]) + __uint_as_float(rr[1]); }
;   l_reg = l_reg * alpha + ps;
;     ...
;   PK4(p0, 0, pa0); PK4(p0, 8, pa1); PK4(p1, 0, pa2); PK4(p1, 8, pa3);
;     ...
; }
; template <int D0> DI void pv_one(f32x16& od, int vb, bf16x8 pa0, bf16x8 pa1, bf16x8 pa2, bf16x8 pa3) {
;   const s16x4 l0 = tr_read<v_rd_off(D0, 0, 0)>(vb), h0 = tr_read<v_rd_off(D0, 0, 1)>(vb), l1 = tr_read<v_rd_off(D0, 1, 0)>(vb), h1 = tr_read<v_rd_off(D0, 1, 1)>(vb);
;   const s16x4 l2 = tr_read<v_rd_off(D0, 2, 0)>(vb), h2 = tr_read<v_rd_off(D0, 2, 1)>(vb), l3 = tr_read<v_rd_off(D0, 3, 0)>(vb), h3 = tr_read<v_rd_off(D0, 3, 1)>(vb);
;   asm volatile("s_waitcnt lgkmcnt(0)" ::: "memory"); SBAR();
;     ...
;   od = __builtin_amdgcn_mfma_f32_32x32x16_bf16(pa0, PK(l0, h0), od, 0, 0, 0);
;   od = __builtin_amdgcn_mfma_f32_32x32x16_bf16(pa1, PK(l1, h1), od, 0, 0, 0);
;   od = __builtin_amdgcn_mfma_f32_32x32x16_bf16(pa2, PK(l2, h2), od, 0, 0, 0);
;   od = __builtin_amdgcn_mfma_f32_32x32x16_bf16(pa3, PK(l3, h3), od, 0, 0, 0);
;     ...
; }
; DI void pv_d0(f32x16* o, int vb, bf16x8 pa0, bf16x8 pa1, bf16x8 pa2, bf16x8 pa3) {
;   pv_one<0>(o[0], vb, pa0, pa1, pa2, pa3); pv_one<1>(o[1], vb, pa0, pa1, pa2, pa3); pv_one<2>(o[2], vb, pa0, pa1, pa2, pa3); pv_one<3>(o[3], vb, pa0, pa1, pa2, pa3);
	v_mfma_f32_32x32x16_bf16 v[80:95], v[214:217], v[98:101], v[80:95]
	v_add_f32_e32 v197, v162, v197
	v_add_f32_e32 v197, v165, v197
	v_add_f32_e32 v197, v161, v197
	v_add_f32_e32 v197, v163, v197
	v_add_f32_e32 v197, v198, v197
	v_add_f32_e32 v197, v199, v197
	s_waitcnt lgkmcnt(2)
	v_mfma_f32_32x32x16_bf16 v[64:79], v[218:221], v[98:101], v[64:79]
	ds_read_b128 v[214:217], v213 offset:32768
	ds_read_b128 v[218:221], v213 offset:36864
	v_add_u32_e32 v213, s6, v184
	v_add_f32_e32 v197, v200, v197
	v_add_f32_e32 v197, v201, v197
	v_add_f32_e32 v197, v202, v197
	v_add_f32_e32 v197, v203, v197
	v_add_f32_e32 v197, v204, v197
	s_waitcnt lgkmcnt(3)
	v_mfma_f32_32x32x16_bf16 v[80:95], v[222:225], v[122:125], v[80:95]
	v_add_u32_e32 v242, 0x6000, v240
	s_mov_b64 s[0:1], 0x1bc20000
	v_lshl_add_u64 v[238:239], v[156:157], 0, s[0:1]
	v_readfirstlane_b32 s2, v242
	s_mov_b32 m0, s2
	v_exp_f32_e32 v241, v209
	global_load_lds_dwordx4 v[238:239], off
	v_add_f32_e32 v197, v205, v197
	s_waitcnt lgkmcnt(2)
	v_mfma_f32_32x32x16_bf16 v[64:79], v[226:229], v[122:125], v[64:79]
	ds_read_b128 v[222:225], v213 offset:32768
	ds_read_b128 v[226:229], v213 offset:36864
	v_add_u32_e32 v213, s6, v185
	v_add_f32_e32 v197, v206, v197
	v_add_f32_e32 v197, v207, v197
	v_add_f32_e32 v197, v235, v197
	v_add_f32_e32 v197, v241, v197
	v_add_f32_e32 v197, v210, v197
	s_waitcnt lgkmcnt(3)
	v_mfma_f32_32x32x16_bf16 v[80:95], v[214:217], v[142:145], v[80:95]
	v_add_f32_e32 v197, v211, v197
	v_add_f32_e32 v197, v212, v197
	v_add_f32_e32 v208, v237, v197
	v_mov_b32_e32 v209, v208
	v_cvt_pk_bf16_f32 v194, v194, v196
	v_cvt_pk_bf16_f32 v195, v192, v195
	s_waitcnt lgkmcnt(2)
	v_mfma_f32_32x32x16_bf16 v[64:79], v[218:221], v[142:145], v[64:79]
	ds_read_b128 v[214:217], v213 offset:32768
	ds_read_b128 v[218:221], v213 offset:36864
	v_permlane32_swap_b32_e32 v208, v209
	v_cvt_pk_bf16_f32 v196, v187, v193
	v_cvt_pk_bf16_f32 v197, v169, v190
	v_cvt_pk_bf16_f32 v166, v166, v168
	v_cvt_pk_bf16_f32 v167, v164, v167
	v_cvt_pk_bf16_f32 v168, v162, v165
	s_waitcnt lgkmcnt(3)
	v_mfma_f32_32x32x16_bf16 v[80:95], v[222:225], v[118:121], v[80:95]
	v_add_u32_e32 v242, 0x8000, v240
	s_mov_b64 s[0:1], 0x1fb46000
	v_lshl_add_u64 v[238:239], v[154:155], 0, s[0:1]
	v_readfirstlane_b32 s2, v242
	s_mov_b32 m0, s2
	v_cvt_pk_bf16_f32 v169, v161, v163
	global_load_lds_dwordx4 v[238:239], off
	s_movk_i32 s0, 0x410
	s_movk_i32 s1, 0x1800
	v_cvt_pk_bf16_f32 v162, v198, v199
	v_cvt_pk_bf16_f32 v163, v200, v201
	s_waitcnt lgkmcnt(2)
	v_mfma_f32_32x32x16_bf16 v[64:79], v[226:229], v[118:121], v[64:79]
	v_cvt_pk_bf16_f32 v164, v202, v203
	v_cvt_pk_bf16_f32 v165, v204, v205
	v_cvt_pk_bf16_f32 v198, v206, v207
	v_cvt_pk_bf16_f32 v199, v235, v241
	v_cvt_pk_bf16_f32 v200, v210, v211
	v_cvt_pk_bf16_f32 v201, v212, v237
	s_waitcnt lgkmcnt(1)
	v_mfma_f32_32x32x16_bf16 v[80:95], v[214:217], v[138:141], v[80:95]
	v_permlane32_swap_b32_e32 v194, v196
	v_permlane32_swap_b32_e32 v195, v197
	v_permlane32_swap_b32_e32 v166, v168
	v_permlane32_swap_b32_e32 v167, v169
	v_permlane32_swap_b32_e32 v162, v164
	v_permlane32_swap_b32_e32 v163, v165
	s_waitcnt lgkmcnt(0)
	v_mfma_f32_32x32x16_bf16 v[64:79], v[218:221], v[138:141], v[64:79]
	v_add_u32_e32 v161, s42, v174
	ds_read_b64_tr_b16 v[202:203], v161 offset:0
	ds_read_b64_tr_b16 v[204:205], v161 offset:0x800
	ds_read_b64_tr_b16 v[210:211], v161 offset:0x1000
	ds_read_b64_tr_b16 v[212:213], v161 offset:0x1800
	ds_read_b64_tr_b16 v[214:215], v161 offset:0x2000
	ds_read_b64_tr_b16 v[216:217], v161 offset:0x2800
	ds_read_b64_tr_b16 v[218:219], v161 offset:0x3000
	ds_read_b64_tr_b16 v[220:221], v161 offset:0x3800
	v_permlane32_swap_b32_e32 v198, v200
	v_permlane32_swap_b32_e32 v199, v201
	v_max_f32_e32 v235, v81, v81
	v_max_f32_e32 v237, v80, v80
	v_max_f32_e32 v235, v237, v235
	s_waitcnt lgkmcnt(6)
	v_mfma_f32_32x32x16_bf16 v[0:15], v[194:197], v[202:205], v[0:15]
	ds_read_b64_tr_b16 v[202:203], v161 offset:0x200
	ds_read_b64_tr_b16 v[204:205], v161 offset:0xa00
	v_max3_f32 v235, v235, v82, v83
	v_max3_f32 v235, v235, v84, v85
	v_max3_f32 v235, v235, v86, v87
	v_max3_f32 v235, v235, v88, v89
	v_max3_f32 v235, v235, v90, v91
	v_max3_f32 v235, v235, v92, v93
	s_waitcnt lgkmcnt(6)
	v_mfma_f32_32x32x16_bf16 v[0:15], v[166:169], v[210:213], v[0:15]
	ds_read_b64_tr_b16 v[210:211], v161 offset:0x1200
	ds_read_b64_tr_b16 v[212:213], v161 offset:0x1a00
	v_max3_f32 v235, v235, v94, v95
	v_max3_f32 v235, v235, v64, v65
	v_max3_f32 v235, v235, v66, v67
	v_max3_f32 v235, v235, v68, v69
	v_max3_f32 v235, v235, v70, v71
	v_max3_f32 v235, v235, v72, v73
	s_waitcnt lgkmcnt(6)
	v_mfma_f32_32x32x16_bf16 v[0:15], v[162:165], v[214:217], v[0:15]
	ds_read_b64_tr_b16 v[214:215], v161 offset:0x2200
	ds_read_b64_tr_b16 v[216:217], v161 offset:0x2a00
	v_max3_f32 v235, v235, v74, v75
	v_max3_f32 v235, v235, v76, v77
	v_max3_f32 v235, v235, v78, v79
	v_mov_b32_e32 v237, v235
	s_waitcnt lgkmcnt(6)
	v_mfma_f32_32x32x16_bf16 v[0:15], v[198:201], v[218:221], v[0:15]
	ds_read_b64_tr_b16 v[218:219], v161 offset:0x3200
	ds_read_b64_tr_b16 v[220:221], v161 offset:0x3a00
	v_permlane32_swap_b32_e32 v235, v237
	v_max_f32_e32 v237, v237, v237
	v_max_f32_e32 v235, v235, v235
	s_waitcnt lgkmcnt(6)
	v_mfma_f32_32x32x16_bf16 v[48:63], v[194:197], v[202:205], v[48:63]
	ds_read_b64_tr_b16 v[202:203], v161 offset:0x400
	ds_read_b64_tr_b16 v[204:205], v161 offset:0xc00
	s_waitcnt lgkmcnt(6)
	v_mfma_f32_32x32x16_bf16 v[48:63], v[166:169], v[210:213], v[48:63]
	ds_read_b64_tr_b16 v[210:211], v161 offset:0x1400
	ds_read_b64_tr_b16 v[212:213], v161 offset:0x1c00
	s_waitcnt lgkmcnt(6)
	v_mfma_f32_32x32x16_bf16 v[48:63], v[162:165], v[214:217], v[48:63]
	ds_read_b64_tr_b16 v[214:215], v161 offset:0x2400
	ds_read_b64_tr_b16 v[216:217], v161 offset:0x2c00
	s_waitcnt lgkmcnt(6)
	v_mfma_f32_32x32x16_bf16 v[48:63], v[198:201], v[218:221], v[48:63]
	ds_read_b64_tr_b16 v[218:219], v161 offset:0x3400
	ds_read_b64_tr_b16 v[220:221], v161 offset:0x3c00
	s_waitcnt lgkmcnt(6)
	v_mfma_f32_32x32x16_bf16 v[32:47], v[194:197], v[202:205], v[32:47]
	ds_read_b64_tr_b16 v[202:203], v161 offset:0x600
	ds_read_b64_tr_b16 v[204:205], v161 offset:0xe00
	s_waitcnt lgkmcnt(6)
	v_mfma_f32_32x32x16_bf16 v[32:47], v[166:169], v[210:213], v[32:47]
	ds_read_b64_tr_b16 v[210:211], v161 offset:0x1600
	ds_read_b64_tr_b16 v[212:213], v161 offset:0x1e00
	s_waitcnt lgkmcnt(6)
	v_mfma_f32_32x32x16_bf16 v[32:47], v[162:165], v[214:217], v[32:47]
	ds_read_b64_tr_b16 v[214:215], v161 offset:0x2600
	ds_read_b64_tr_b16 v[216:217], v161 offset:0x2e00
	s_waitcnt lgkmcnt(6)
	v_mfma_f32_32x32x16_bf16 v[32:47], v[198:201], v[218:221], v[32:47]
	ds_read_b64_tr_b16 v[218:219], v161 offset:0x3600
	ds_read_b64_tr_b16 v[220:221], v161 offset:0x3e00
	v_max_f32_e32 v161, v235, v237
	v_sub_f32_e32 v237, v161, v160
	s_waitcnt vmcnt(0)
	s_waitcnt vmcnt(0)
	s_waitcnt lgkmcnt(0)
	s_barrier
; #define SBAR() __builtin_amdgcn_sched_barrier(0)
; template <int OFF> DI s16x4 tr_read(int vb) { s16x4 r; asm volatile("ds_read_b64_tr_b16 %0, %1 offset:%2" : "=&v"(r) : "v"(vb), "i"(OFF) : "memory"); return r; }
; DI void partialSM(f32x16& p0, f32x16& p1, float& m_reg, float& mn, float& alpha) {
;   constexpr float C = ATT_SCALE * 1.4426950408889634f;
;   float pmax = p0[0];
; #pragma unroll
;   for (int r = 1; r < 16; ++r) pmax = fmaxf(pmax, p0[r]);
; #pragma unroll
;   for (int r = 0; r < 16; ++r) pmax = fmaxf(pmax, p1[r]);
;   { auto rr = __builtin_amdgcn_permlane32_swap(__float_as_uint(pmax), __float_as_uint(pmax), false, false);
;     pmax = fmaxf(__uint_as_float(rr[0]), __uint_as_float(rr[1])); }
;   if (__builtin_expect(__all(pmax - m_reg <= ATT_THR / ATT_SCALE), 1)) { mn = m_reg; alpha = 1.f; }
;   else { mn = fmaxf(m_reg, pmax); alpha = __builtin_amdgcn_exp2f((m_reg - mn) * C); m_reg = mn; }
; template <int D0> DI void pv_one(f32x16& od, int vb, bf16x8 pa0, bf16x8 pa1, bf16x8 pa2, bf16x8 pa3) {
;   const s16x4 l0 = tr_read<v_rd_off(D0, 0, 0)>(vb), h0 = tr_read<v_rd_off(D0, 0, 1)>(vb), l1 = tr_read<v_rd_off(D0, 1, 0)>(vb), h1 = tr_read<v_rd_off(D0, 1, 1)>(vb);
;   const s16x4 l2 = tr_read<v_rd_off(D0, 2, 0)>(vb), h2 = tr_read<v_rd_off(D0, 2, 1)>(vb), l3 = tr_read<v_rd_off(D0, 3, 0)>(vb), h3 = tr_read<v_rd_off(D0, 3, 1)>(vb);
;   asm volatile("s_waitcnt lgkmcnt(0)" ::: "memory"); SBAR();
;     ...
;   od = __builtin_amdgcn_mfma_f32_32x32x16_bf16(pa0, PK(l0, h0), od, 0, 0, 0);
;   od = __builtin_amdgcn_mfma_f32_32x32x16_bf16(pa1, PK(l1, h1), od, 0, 0, 0);
;   od = __builtin_amdgcn_mfma_f32_32x32x16_bf16(pa2, PK(l2, h2), od, 0, 0, 0);
;   od = __builtin_amdgcn_mfma_f32_32x32x16_bf16(pa3, PK(l3, h3), od, 0, 0, 0);
;     ...
; }
; DI void pv_d0(f32x16* o, int vb, bf16x8 pa0, bf16x8 pa1, bf16x8 pa2, bf16x8 pa3) {
;   pv_one<0>(o[0], vb, pa0, pa1, pa2, pa3); pv_one<1>(o[1], vb, pa0, pa1, pa2, pa3); pv_one<2>(o[2], vb, pa0, pa1, pa2, pa3); pv_one<3>(o[3], vb, pa0, pa1, pa2, pa3);
	v_mfma_f32_32x32x16_bf16 v[16:31], v[194:197], v[202:205], v[16:31]
	v_mfma_f32_32x32x16_bf16 v[16:31], v[166:169], v[210:213], v[16:31]
	v_mfma_f32_32x32x16_bf16 v[16:31], v[162:165], v[214:217], v[16:31]
	v_mfma_f32_32x32x16_bf16 v[16:31], v[198:201], v[218:221], v[16:31]
	v_cmp_ge_f32_e32 vcc, s65, v237
	s_cmp_eq_u64 vcc, exec
	s_cselect_b64 s[38:39], -1, 0
	s_cmp_ge_u32 s12, s52
	s_cselect_b64 s[42:43], -1, 0
	s_and_b64 vcc, exec, s[42:43]
	s_branch .Lattn_bb2_join
